# in-projection: tiles after a workgroup's first two handed out from a per-layer per-XCD counter (ticket taken one tile ahead, parked in LDS); faster workgroups take more tiles
# speedup vs baseline: 1.0009x; 1.0009x over previous
; DI void phase_inproj(const Params& p, int layer, char* lds) {
;     ...
;   const bool xcd_ok = (gridDim.x % 8) == 0;
;   const int xj = xcd_ok ? (int)(blockIdx.x & 7) : 0, nbl = xcd_ok ? (int)(gridDim.x >> 3) : (int)gridDim.x;
;   const int bl = xcd_ok ? (int)(blockIdx.x >> 3) : (int)blockIdx.x, per_x = xcd_ok ? NTILES / 8 : NTILES;
;   for (int u = bl; u < per_x; u += nbl) {
;     const int lr = u / NTN, nt = u % NTN;
;     const int mt = xcd_ok ? lr * 8 + xj : lr, m0 = mt * 256, n0 = nt * 256;
.LBB0_79:
	v_readlane_b32 s4, v255, 22
	v_readlane_b32 s5, v255, 23
	s_mov_b32 s81, s5
	v_readlane_b32 s4, v254, 33
	v_readlane_b32 s5, v254, 34
	v_mov_b32_e32 v0, v184
	s_andn2_b64 vcc, exec, s[4:5]
	s_cbranch_vccnz .LBB0_152
	v_lshrrev_b32_e32 v1, 1, v0
	s_mul_i32 s5, s80, 0x570000
	v_and_b32_e32 v131, 0x60, v1
	v_ashrrev_i32_e32 v1, 2, v0
	s_mul_hi_u32 s4, s80, 0x570000
	s_add_u32 s20, s34, s5
	v_and_b32_e32 v130, 15, v0
	v_and_b32_e32 v1, 0xffffffc0, v1
	v_lshrrev_b32_e32 v0, 2, v0
	s_addc_u32 s21, s35, s4
	v_and_or_b32 v144, v0, 12, v1
	v_readlane_b32 s23, v254, 53
	s_mov_b32 s32, 0
	s_nop 0
	v_writelane_b32 v255, s32, 45
	s_branch .LBB0_82
.LBB0_81:
	s_or_b64 exec, exec, s[4:5]
	v_readlane_b32 s23, v255, 44
	v_readlane_b32 s4, v254, 32
	s_cmp_lt_i32 s23, s4
	s_cbranch_scc0 .LBB0_152

; DI void phase_inproj(const Params& p, int layer, char* lds) {
;     ...
;   for (int u = bl; u < per_x; u += nbl) {
;     const int lr = u / NTN, nt = u % NTN;
;     const int mt = xcd_ok ? lr * 8 + xj : lr, m0 = mt * 256, n0 = nt * 256;
.LBB0_88:
	s_or_b64 exec, exec, s[8:9]
	s_mov_b32 s32, 0
	s_add_i32 s7, s23, s63
	s_cmp_lt_u32 s23, s63
	s_cbranch_scc1 .Ldt_have
	v_readlane_b32 s13, v255, 45
	s_nop 3
	v_mov_b32_e32 v176, 0x23fe8
	v_add_u32_e32 v176, s13, v176
	ds_read_b32 v176, v176
	s_xor_b32 s13, s13, 4
	s_nop 0
	v_writelane_b32 v255, s13, 45
	s_waitcnt lgkmcnt(0)
	s_nop 0
	v_readfirstlane_b32 s7, v176
	s_nop 3
.Ldt_have:
	v_writelane_b32 v255, s7, 44
	v_readlane_b32 s12, v254, 32
	v_lshlrev_b32_e32 v150, 4, v184
	s_cmp_lt_i32 s7, s12
	s_cbranch_scc0 .Lipf_none
	s_mov_b32 s32, 1
	s_mul_hi_i32 s12, s7, 0x2e8ba2e9
	s_lshr_b32 s13, s12, 31
	s_ashr_i32 s12, s12, 1
	s_add_i32 s12, s12, s13
	s_mul_i32 s13, s12, 11
	s_sub_i32 s13, s7, s13
	s_lshl_b32 s13, s13, 19
	s_lshl_b32 s24, s12, 3
	s_or_b32 s24, s24, s28
	v_readlane_b32 s10, v254, 30
	v_readlane_b32 s11, v254, 31
	v_lshrrev_b32_e32 v151, 10, v150
	v_and_b32_e32 v152, 0x3ff, v150
	s_and_b64 s[10:11], s[10:11], exec
	s_cselect_b32 s24, s24, s12
	s_lshl_b32 s24, s24, 19
	s_add_u32 s10, s20, s13
	s_addc_u32 s11, s21, 0
	s_add_u32 s12, s78, s24
	s_addc_u32 s13, s79, 0
	v_lshrrev_b32_e32 v153, 4, v152
	v_and_b32_e32 v153, 32, v153
	v_xor_b32_e32 v152, v152, v153
	v_lshrrev_b32_e32 v153, 1, v151
	v_lshlrev_b32_e32 v153, 4, v153
	v_lshrrev_b32_e32 v154, 6, v152
	v_add_u32_e32 v153, v153, v154
	v_and_b32_e32 v154, 1, v151
	v_lshlrev_b32_e32 v154, 5, v154
	v_bfe_u32 v155, v152, 1, 5
	v_add_u32_e32 v154, v154, v155
	v_lshl_add_u32 v153, v153, 10, v154
	v_lshlrev_b32_e32 v156, 1, v153
	v_mov_b32_e32 v157, 0
	v_add_u32_e32 v158, 0x20000, v156
	v_mov_b32_e32 v159, 0
	v_readfirstlane_b32 s25, v150
	v_readlane_b32 s26, v255, 7
	v_readlane_b32 s27, v255, 8
	v_lshl_add_u64 v[160:161], s[10:11], 0, v[156:157]
	v_lshl_add_u64 v[162:163], s[10:11], 0, v[158:159]
	v_lshl_add_u64 v[164:165], s[12:13], 0, v[156:157]
	v_lshl_add_u64 v[166:167], s[12:13], 0, v[158:159]
	s_add_u32 s10, s10, 0x40000
	s_addc_u32 s11, s11, 0
	s_add_u32 s12, s12, 0x40000
	s_addc_u32 s13, s13, 0
	v_lshl_add_u64 v[168:169], s[10:11], 0, v[156:157]
	v_lshl_add_u64 v[170:171], s[10:11], 0, v[158:159]
	v_lshl_add_u64 v[172:173], s[12:13], 0, v[156:157]
	v_lshl_add_u64 v[174:175], s[12:13], 0, v[158:159]
	s_add_u32 s7, s26, s25
	s_mov_b32 m0, s7
	s_nop 0
	global_load_lds_dwordx4 v[160:161], off
	s_add_u32 s7, s7, 0x2000
	s_mov_b32 m0, s7
	s_nop 0
	global_load_lds_dwordx4 v[162:163], off
	s_mov_b32 m0, s25
	s_nop 0
	global_load_lds_dwordx4 v[164:165], off
	s_add_u32 s7, s25, 0x2000
	s_mov_b32 m0, s7
	s_nop 0
	global_load_lds_dwordx4 v[166:167], off
	s_add_u32 s7, s27, s25
	s_mov_b32 m0, s7
	s_nop 0
	global_load_lds_dwordx4 v[168:169], off
	s_add_u32 s7, s7, 0x2000
	s_mov_b32 m0, s7
	s_nop 0
	global_load_lds_dwordx4 v[170:171], off
	s_add_u32 s7, s25, 0x4000
	s_mov_b32 m0, s7
	s_nop 0
	global_load_lds_dwordx4 v[172:173], off
	s_add_u32 s7, s25, 0x6000
	s_mov_b32 m0, s7
	s_nop 0
	global_load_lds_dwordx4 v[174:175], off
	v_readfirstlane_b32 s7, v184
	s_nop 3
	s_cmp_lg_u32 s7, 0
	s_cbranch_scc1 .Lipf_none
	v_readlane_b32 s10, v255, 36
	v_readlane_b32 s11, v255, 37
	s_lshl_b32 s12, s80, 5
	s_lshl_b32 s13, s28, 2
	s_add_i32 s12, s12, s13
	s_addk_i32 s12, 0x80
	s_add_u32 s10, s10, s12
	s_addc_u32 s11, s11, 0
	v_mov_b32_e32 v181, 1
	s_mov_b64 s[12:13], exec
	s_mov_b64 exec, 1
	global_atomic_add v180, v5, v181, s[10:11] sc0
	s_mov_b64 exec, s[12:13]

; DI void phase_inproj(const Params& p, int layer, char* lds) {
;     ...
;   for (int u = bl; u < per_x; u += nbl) {
;     const int lr = u / NTN, nt = u % NTN;
;     const int mt = xcd_ok ? lr * 8 + xj : lr, m0 = mt * 256, n0 = nt * 256;
.Lipe3_done:
	s_cmp_eq_u32 s32, 0
	s_cbranch_scc1 .Ldt_nowr
	v_readfirstlane_b32 s5, v184
	s_nop 3
	s_cmp_lg_u32 s5, 0
	s_cbranch_scc1 .Ldt_nowr
	s_waitcnt vmcnt(63)
	v_readlane_b32 s5, v255, 45
	s_nop 3
	s_mov_b64 s[8:9], exec
	s_mov_b64 exec, 1
	v_mov_b32_e32 v182, 0x23fe8
	v_add_u32_e32 v182, s5, v182
	v_add_u32_e32 v180, 64, v180
	ds_write_b32 v182, v180
	s_waitcnt lgkmcnt(0)
	s_mov_b64 exec, s[8:9]
